# P8 H requant loop: all 12 loads of an item issued up front with one wait (was four dependent load round trips)
# speedup vs baseline: 1.0044x; 1.0044x over previous
.LBB0_800:
	s_ashr_i32 s2, s11, 31
	s_lshr_b32 s2, s2, 25
	s_add_i32 s3, s11, s2
	s_ashr_i32 s2, s3, 7
	s_lshl_b32 s7, s2, 8
	s_and_b32 s6, s3, 0xffffff80
	s_ashr_i32 s3, s2, 31
	s_sub_i32 s12, s10, s7
	s_lshl_b64 s[8:9], s[2:3], 8
	s_ashr_i32 s13, s12, 31
	s_add_u32 s8, s8, s12
	s_addc_u32 s9, s9, s13
	v_mov_b32_e32 v3, s9
	v_or_b32_e32 v2, s8, v36
	v_lshlrev_b64 v[2:3], 15, v[2:3]
	v_lshl_add_u64 v[26:27], v[38:39], 0, v[2:3]
	v_add_u32_e32 v2, s7, v34
	v_ashrrev_i32_e32 v3, 31, v2
	v_lshl_add_u64 v[42:43], v[2:3], 2, s[42:43]
	global_load_dwordx4 v[10:13], v[26:27], off offset:16
	global_load_dwordx4 v[14:17], v[26:27], off
	global_load_dword v1, v[42:43], off
	s_lshl_b64 s[8:9], s[2:3], 22
	s_ashr_i32 s7, s6, 31
	v_add_co_u32_e32 v4, vcc, s83, v26
	s_mov_b64 s[2:3], 0x4000
	v_lshl_add_u64 v[2:3], v[26:27], 0, s[24:25]
	v_addc_co_u32_e32 v5, vcc, 0, v27, vcc
	global_load_dwordx4 v[6:9], v[4:5], off
	v_add_co_u32_e32 v20, vcc, s77, v26
	global_load_dwordx4 v[2:5], v[2:3], off offset:16
	v_lshl_add_u64 v[18:19], v[26:27], 0, s[2:3]
	global_load_dword v56, v[42:43], off offset:256
	v_addc_co_u32_e32 v21, vcc, 0, v27, vcc
	s_mov_b64 s[2:3], 0x6000
	global_load_dwordx4 v[22:25], v[20:21], off
	s_nop 0
	global_load_dwordx4 v[18:21], v[18:19], off offset:16
	global_load_dword v62, v[42:43], off offset:512
	v_lshl_add_u64 v[28:29], v[26:27], 0, s[2:3]
	s_movk_i32 s2, 0x6000
	v_add_co_u32_e32 v26, vcc, s2, v26
	s_nop 1
	v_addc_co_u32_e32 v27, vcc, 0, v27, vcc
	global_load_dwordx4 v[30:33], v[26:27], off
	s_nop 0
	global_load_dwordx4 v[26:29], v[28:29], off offset:16
	global_load_dword v42, v[42:43], off offset:768
	s_waitcnt vmcnt(0)
	v_lshlrev_b32_e32 v49, 16, v10
	v_and_b32_e32 v50, 0xffff0000, v10
	v_mul_f32_e32 v1, v1, v1
	v_mul_f32_e32 v1, 0x3f810000, v1
	v_max_f32_e32 v1, 0xda24260, v1
	v_div_scale_f32 v57, s[2:3], v1, v1, s56
	v_rcp_f32_e32 v58, v57
	v_lshlrev_b32_e32 v51, 16, v11
	v_and_b32_e32 v52, 0xffff0000, v11
	v_lshlrev_b32_e32 v53, 16, v12
	v_fma_f32 v59, -v57, v58, 1.0
	v_fmac_f32_e32 v58, v59, v58
	v_div_scale_f32 v59, vcc, s56, v1, s56
	v_mul_f32_e32 v60, v59, v58
	v_fma_f32 v61, -v57, v60, v59
	v_fmac_f32_e32 v60, v61, v58
	v_fma_f32 v57, -v57, v60, v59
	v_div_fmas_f32 v57, v57, v58, v60
	v_div_fixup_f32 v35, v57, v1, s56
	v_and_b32_e32 v54, 0xffff0000, v12
	v_lshlrev_b32_e32 v48, 16, v17
	v_and_b32_e32 v17, 0xffff0000, v17
	v_lshlrev_b32_e32 v55, 16, v13
	v_and_b32_e32 v13, 0xffff0000, v13
	v_mul_f32_e32 v13, v35, v13
	v_rndne_f32_e32 v13, v13
	v_cvt_i32_f32_e32 v13, v13
	v_med3_i32 v13, v13, 0, v212
	v_lshlrev_b32_e32 v13, 24, v13
	v_mul_f32_e32 v1, v56, v56
	v_mul_f32_e32 v1, 0x3f810000, v1
	v_max_f32_e32 v1, 0xda24260, v1
	v_div_scale_f32 v57, s[2:3], v1, v1, s56
	v_rcp_f32_e32 v58, v57
	s_nop 0
	v_fma_f32 v59, -v57, v58, 1.0
	v_fmac_f32_e32 v58, v59, v58
	v_div_scale_f32 v59, vcc, s56, v1, s56
	v_mul_f32_e32 v60, v59, v58
	v_fma_f32 v61, -v57, v60, v59
	v_fmac_f32_e32 v60, v61, v58
	v_fma_f32 v57, -v57, v60, v59
	v_div_fmas_f32 v57, v57, v58, v60
	v_div_fixup_f32 v1, v57, v1, s56
	v_mul_f32_e32 v62, v62, v62
	v_mul_f32_e32 v62, 0x3f810000, v62
	v_max_f32_e32 v62, 0xda24260, v62
	v_div_scale_f32 v57, s[2:3], v62, v62, s56
	v_rcp_f32_e32 v58, v57
	s_nop 0
	v_fma_f32 v59, -v57, v58, 1.0
	v_fmac_f32_e32 v58, v59, v58
	v_div_scale_f32 v59, vcc, s56, v62, s56
	v_mul_f32_e32 v60, v59, v58
	v_fma_f32 v61, -v57, v60, v59
	v_fmac_f32_e32 v60, v61, v58
	v_fma_f32 v57, -v57, v60, v59
	v_div_fmas_f32 v57, v57, v58, v60
	v_div_fixup_f32 v37, v57, v62, s56
	v_mul_f32_e32 v42, v42, v42
	v_mul_f32_e32 v42, 0x3f810000, v42
	v_max_f32_e32 v42, 0xda24260, v42
	v_div_scale_f32 v43, s[2:3], v42, v42, s56
	v_rcp_f32_e32 v44, v43
	s_lshl_b64 s[2:3], s[6:7], 15
	s_sub_u32 s2, s8, s2
	s_subb_u32 s3, s9, s3
	v_fma_f32 v45, -v43, v44, 1.0
	v_fmac_f32_e32 v44, v45, v44
	v_div_scale_f32 v45, vcc, s56, v42, s56
	v_mul_f32_e32 v46, v45, v44
	v_fma_f32 v47, -v43, v46, v45
	v_fmac_f32_e32 v46, v47, v44
	v_fma_f32 v43, -v43, v46, v45
	v_lshlrev_b32_e32 v45, 16, v14
	v_and_b32_e32 v14, 0xffff0000, v14
	v_div_fmas_f32 v43, v43, v44, v46
	v_lshlrev_b32_e32 v46, 16, v15
	v_and_b32_e32 v15, 0xffff0000, v15
	v_mul_f32_e32 v10, v35, v45
	v_mul_f32_e32 v11, v35, v14
	v_rndne_f32_e32 v10, v10
	v_rndne_f32_e32 v11, v11
	v_mul_f32_e32 v12, v35, v46
	v_mul_f32_e32 v14, v35, v15
	v_cvt_i32_f32_e32 v10, v10
	v_cvt_i32_f32_e32 v11, v11
	v_rndne_f32_e32 v12, v12
	v_rndne_f32_e32 v14, v14
	v_cvt_i32_f32_e32 v12, v12
	v_cvt_i32_f32_e32 v14, v14
	v_med3_i32 v10, v10, 0, v212
	v_med3_i32 v11, v11, 0, v212
	v_lshlrev_b32_e32 v47, 16, v16
	v_and_b32_e32 v16, 0xffff0000, v16
	v_med3_i32 v12, v12, 0, v212
	v_med3_i32 v14, v14, 0, v212
	v_lshl_or_b32 v10, v11, 8, v10
	v_lshl_or_b32 v10, v12, 16, v10
	v_lshlrev_b32_e32 v11, 24, v14
	v_mul_f32_e32 v12, v35, v16
	v_mul_f32_e32 v14, v35, v48
	v_bitop3_b32 v10, v10, s57, v11 bitop3:0x36
	v_mul_f32_e32 v11, v35, v47
	v_rndne_f32_e32 v12, v12
	v_rndne_f32_e32 v14, v14
	v_mul_f32_e32 v15, v35, v17
	v_rndne_f32_e32 v11, v11
	v_cvt_i32_f32_e32 v12, v12
	v_cvt_i32_f32_e32 v14, v14
	v_rndne_f32_e32 v15, v15
	v_cvt_i32_f32_e32 v11, v11
	v_cvt_i32_f32_e32 v15, v15
	v_med3_i32 v12, v12, 0, v212
	v_med3_i32 v14, v14, 0, v212
	v_med3_i32 v11, v11, 0, v212
	v_med3_i32 v15, v15, 0, v212
	v_lshlrev_b32_e32 v12, 8, v12
	v_lshlrev_b32_e32 v14, 16, v14
	v_or3_b32 v11, v12, v11, v14
	v_lshlrev_b32_e32 v12, 24, v15
	v_bitop3_b32 v11, v11, s57, v12 bitop3:0x36
	v_mul_f32_e32 v12, v35, v49
	v_mul_f32_e32 v14, v35, v50
	v_rndne_f32_e32 v12, v12
	v_rndne_f32_e32 v14, v14
	v_mul_f32_e32 v15, v35, v51
	v_mul_f32_e32 v16, v35, v52
	v_cvt_i32_f32_e32 v12, v12
	v_cvt_i32_f32_e32 v14, v14
	v_rndne_f32_e32 v15, v15
	v_rndne_f32_e32 v16, v16
	v_cvt_i32_f32_e32 v15, v15
	v_cvt_i32_f32_e32 v16, v16
	v_med3_i32 v12, v12, 0, v212
	v_med3_i32 v14, v14, 0, v212
	v_med3_i32 v15, v15, 0, v212
	v_med3_i32 v16, v16, 0, v212
	v_lshl_or_b32 v12, v14, 8, v12
	v_lshl_or_b32 v12, v15, 16, v12
	v_lshlrev_b32_e32 v14, 24, v16
	v_mul_f32_e32 v15, v35, v54
	v_mul_f32_e32 v16, v35, v55
	v_bitop3_b32 v12, v12, s57, v14 bitop3:0x36
	v_mul_f32_e32 v14, v35, v53
	v_rndne_f32_e32 v15, v15
	v_rndne_f32_e32 v16, v16
	v_rndne_f32_e32 v14, v14
	v_cvt_i32_f32_e32 v15, v15
	v_cvt_i32_f32_e32 v16, v16
	v_cvt_i32_f32_e32 v14, v14
	v_div_fixup_f32 v44, v43, v42, s56
	v_med3_i32 v15, v15, 0, v212
	v_med3_i32 v16, v16, 0, v212
	v_med3_i32 v14, v14, 0, v212
	v_lshlrev_b32_e32 v15, 8, v15
	v_lshlrev_b32_e32 v16, 16, v16
	v_or3_b32 v14, v15, v14, v16
	v_lshl_add_u64 v[42:43], v[40:41], 0, s[2:3]
	v_bitop3_b32 v13, v14, s57, v13 bitop3:0x36
	global_store_dwordx4 v[42:43], v[10:13], off
	v_lshlrev_b32_e32 v14, 16, v2
	v_and_b32_e32 v15, 0xffff0000, v2
	v_lshlrev_b32_e32 v10, 16, v6
	v_and_b32_e32 v6, 0xffff0000, v6
	v_lshlrev_b32_e32 v11, 16, v7
	v_and_b32_e32 v7, 0xffff0000, v7
	v_lshlrev_b32_e32 v16, 16, v3
	v_and_b32_e32 v17, 0xffff0000, v3
	v_mul_f32_e32 v2, v1, v10
	v_mul_f32_e32 v3, v1, v6
	v_lshlrev_b32_e32 v35, 16, v4
	v_and_b32_e32 v45, 0xffff0000, v4
	v_rndne_f32_e32 v2, v2
	v_rndne_f32_e32 v3, v3
	v_mul_f32_e32 v4, v1, v11
	v_mul_f32_e32 v6, v1, v7
	v_cvt_i32_f32_e32 v2, v2
	v_cvt_i32_f32_e32 v3, v3
	v_rndne_f32_e32 v4, v4
	v_rndne_f32_e32 v6, v6
	v_cvt_i32_f32_e32 v4, v4
	v_cvt_i32_f32_e32 v6, v6
	v_med3_i32 v2, v2, 0, v212
	v_med3_i32 v3, v3, 0, v212
	v_lshlrev_b32_e32 v12, 16, v8
	v_and_b32_e32 v8, 0xffff0000, v8
	v_lshlrev_b32_e32 v13, 16, v9
	v_med3_i32 v4, v4, 0, v212
	v_med3_i32 v6, v6, 0, v212
	v_lshl_or_b32 v2, v3, 8, v2
	v_and_b32_e32 v9, 0xffff0000, v9
	v_lshl_or_b32 v2, v4, 16, v2
	v_lshlrev_b32_e32 v3, 24, v6
	v_mul_f32_e32 v4, v1, v8
	v_mul_f32_e32 v6, v1, v13
	v_bitop3_b32 v2, v2, s57, v3 bitop3:0x36
	v_mul_f32_e32 v3, v1, v12
	v_rndne_f32_e32 v4, v4
	v_rndne_f32_e32 v6, v6
	v_mul_f32_e32 v7, v1, v9
	v_rndne_f32_e32 v3, v3
	v_cvt_i32_f32_e32 v4, v4
	v_cvt_i32_f32_e32 v6, v6
	v_rndne_f32_e32 v7, v7
	v_cvt_i32_f32_e32 v3, v3
	v_cvt_i32_f32_e32 v7, v7
	v_med3_i32 v4, v4, 0, v212
	v_med3_i32 v6, v6, 0, v212
	v_med3_i32 v3, v3, 0, v212
	v_med3_i32 v7, v7, 0, v212
	v_lshlrev_b32_e32 v4, 8, v4
	v_lshlrev_b32_e32 v6, 16, v6
	v_or3_b32 v3, v4, v3, v6
	v_lshlrev_b32_e32 v4, 24, v7
	v_bitop3_b32 v3, v3, s57, v4 bitop3:0x36
	v_mul_f32_e32 v4, v1, v14
	v_mul_f32_e32 v6, v1, v15
	v_rndne_f32_e32 v4, v4
	v_rndne_f32_e32 v6, v6
	v_mul_f32_e32 v7, v1, v16
	v_mul_f32_e32 v8, v1, v17
	v_cvt_i32_f32_e32 v4, v4
	v_cvt_i32_f32_e32 v6, v6
	v_rndne_f32_e32 v7, v7
	v_rndne_f32_e32 v8, v8
	v_cvt_i32_f32_e32 v7, v7
	v_cvt_i32_f32_e32 v8, v8
	v_med3_i32 v4, v4, 0, v212
	v_med3_i32 v6, v6, 0, v212
	v_lshlrev_b32_e32 v46, 16, v5
	v_med3_i32 v7, v7, 0, v212
	v_med3_i32 v8, v8, 0, v212
	v_lshl_or_b32 v4, v6, 8, v4
	v_and_b32_e32 v5, 0xffff0000, v5
	v_lshl_or_b32 v4, v7, 16, v4
	v_lshlrev_b32_e32 v6, 24, v8
	v_mul_f32_e32 v7, v1, v45
	v_mul_f32_e32 v8, v1, v46
	v_bitop3_b32 v4, v4, s57, v6 bitop3:0x36
	v_mul_f32_e32 v6, v1, v35
	v_rndne_f32_e32 v7, v7
	v_rndne_f32_e32 v8, v8
	v_mul_f32_e32 v1, v1, v5
	v_rndne_f32_e32 v6, v6
	v_cvt_i32_f32_e32 v7, v7
	v_cvt_i32_f32_e32 v8, v8
	v_rndne_f32_e32 v1, v1
	v_cvt_i32_f32_e32 v6, v6
	v_cvt_i32_f32_e32 v1, v1
	v_med3_i32 v7, v7, 0, v212
	v_med3_i32 v8, v8, 0, v212
	v_med3_i32 v6, v6, 0, v212
	v_med3_i32 v1, v1, 0, v212
	v_lshlrev_b32_e32 v5, 8, v7
	v_lshlrev_b32_e32 v7, 16, v8
	v_or3_b32 v5, v5, v6, v7
	v_lshlrev_b32_e32 v1, 24, v1
	v_add_co_u32_e32 v6, vcc, s83, v42
	v_bitop3_b32 v5, v5, s57, v1 bitop3:0x36
	s_nop 0
	v_addc_co_u32_e32 v7, vcc, 0, v43, vcc
	global_store_dwordx4 v[6:7], v[2:5], off
	v_lshlrev_b32_e32 v1, 16, v22
	v_mul_f32_e32 v1, v37, v1
	v_and_b32_e32 v2, 0xffff0000, v22
	v_lshlrev_b32_e32 v3, 16, v23
	v_and_b32_e32 v4, 0xffff0000, v23
	v_mul_f32_e32 v2, v37, v2
	v_rndne_f32_e32 v1, v1
	v_rndne_f32_e32 v2, v2
	v_mul_f32_e32 v3, v37, v3
	v_mul_f32_e32 v4, v37, v4
	v_cvt_i32_f32_e32 v1, v1
	v_cvt_i32_f32_e32 v2, v2
	v_rndne_f32_e32 v3, v3
	v_rndne_f32_e32 v4, v4
	v_cvt_i32_f32_e32 v3, v3
	v_cvt_i32_f32_e32 v4, v4
	v_med3_i32 v1, v1, 0, v212
	v_med3_i32 v2, v2, 0, v212
	v_and_b32_e32 v6, 0xffff0000, v24
	v_lshlrev_b32_e32 v7, 16, v25
	v_med3_i32 v3, v3, 0, v212
	v_med3_i32 v4, v4, 0, v212
	v_lshl_or_b32 v1, v2, 8, v1
	v_lshlrev_b32_e32 v5, 16, v24
	v_and_b32_e32 v8, 0xffff0000, v25
	v_lshl_or_b32 v1, v3, 16, v1
	v_lshlrev_b32_e32 v2, 24, v4
	v_mul_f32_e32 v3, v37, v6
	v_mul_f32_e32 v4, v37, v7
	v_bitop3_b32 v2, v1, s57, v2 bitop3:0x36
	v_mul_f32_e32 v1, v37, v5
	v_rndne_f32_e32 v3, v3
	v_rndne_f32_e32 v4, v4
	v_mul_f32_e32 v5, v37, v8
	v_rndne_f32_e32 v1, v1
	v_cvt_i32_f32_e32 v3, v3
	v_cvt_i32_f32_e32 v4, v4
	v_rndne_f32_e32 v5, v5
	v_cvt_i32_f32_e32 v1, v1
	v_cvt_i32_f32_e32 v5, v5
	v_med3_i32 v3, v3, 0, v212
	v_med3_i32 v4, v4, 0, v212
	v_med3_i32 v1, v1, 0, v212
	v_med3_i32 v5, v5, 0, v212
	v_lshlrev_b32_e32 v3, 8, v3
	v_lshlrev_b32_e32 v4, 16, v4
	v_lshlrev_b32_e32 v9, 16, v18
	v_and_b32_e32 v10, 0xffff0000, v18
	v_or3_b32 v1, v3, v1, v4
	v_lshlrev_b32_e32 v3, 24, v5
	v_lshlrev_b32_e32 v11, 16, v19
	v_and_b32_e32 v12, 0xffff0000, v19
	v_bitop3_b32 v3, v1, s57, v3 bitop3:0x36
	v_mul_f32_e32 v1, v37, v9
	v_mul_f32_e32 v4, v37, v10
	v_rndne_f32_e32 v1, v1
	v_rndne_f32_e32 v4, v4
	v_mul_f32_e32 v5, v37, v11
	v_mul_f32_e32 v6, v37, v12
	v_cvt_i32_f32_e32 v1, v1
	v_cvt_i32_f32_e32 v4, v4
	v_rndne_f32_e32 v5, v5
	v_rndne_f32_e32 v6, v6
	v_cvt_i32_f32_e32 v5, v5
	v_cvt_i32_f32_e32 v6, v6
	v_med3_i32 v1, v1, 0, v212
	v_med3_i32 v4, v4, 0, v212
	v_and_b32_e32 v14, 0xffff0000, v20
	v_lshlrev_b32_e32 v15, 16, v21
	v_med3_i32 v5, v5, 0, v212
	v_med3_i32 v6, v6, 0, v212
	v_lshl_or_b32 v1, v4, 8, v1
	v_lshlrev_b32_e32 v13, 16, v20
	v_and_b32_e32 v16, 0xffff0000, v21
	v_lshl_or_b32 v1, v5, 16, v1
	v_lshlrev_b32_e32 v4, 24, v6
	v_mul_f32_e32 v5, v37, v14
	v_mul_f32_e32 v6, v37, v15
	v_bitop3_b32 v4, v1, s57, v4 bitop3:0x36
	v_mul_f32_e32 v1, v37, v13
	v_rndne_f32_e32 v5, v5
	v_rndne_f32_e32 v6, v6
	v_mul_f32_e32 v7, v37, v16
	v_rndne_f32_e32 v1, v1
	v_cvt_i32_f32_e32 v5, v5
	v_cvt_i32_f32_e32 v6, v6
	v_rndne_f32_e32 v7, v7
	v_cvt_i32_f32_e32 v1, v1
	v_cvt_i32_f32_e32 v7, v7
	v_med3_i32 v5, v5, 0, v212
	v_med3_i32 v6, v6, 0, v212
	v_med3_i32 v1, v1, 0, v212
	v_med3_i32 v7, v7, 0, v212
	v_lshlrev_b32_e32 v5, 8, v5
	v_lshlrev_b32_e32 v6, 16, v6
	v_or3_b32 v1, v5, v1, v6
	v_lshlrev_b32_e32 v5, 24, v7
	v_add_co_u32_e32 v6, vcc, s77, v42
	v_bitop3_b32 v5, v1, s57, v5 bitop3:0x36
	s_nop 0
	v_addc_co_u32_e32 v7, vcc, 0, v43, vcc
	global_store_dwordx4 v[6:7], v[2:5], off
	v_lshlrev_b32_e32 v1, 16, v30
	v_mul_f32_e32 v1, v44, v1
	v_and_b32_e32 v2, 0xffff0000, v30
	v_lshlrev_b32_e32 v3, 16, v31
	v_and_b32_e32 v4, 0xffff0000, v31
	v_mul_f32_e32 v2, v44, v2
	v_rndne_f32_e32 v1, v1
	v_rndne_f32_e32 v2, v2
	v_mul_f32_e32 v3, v44, v3
	v_mul_f32_e32 v4, v44, v4
	v_cvt_i32_f32_e32 v1, v1
	v_cvt_i32_f32_e32 v2, v2
	v_rndne_f32_e32 v3, v3
	v_rndne_f32_e32 v4, v4
	v_cvt_i32_f32_e32 v3, v3
	v_cvt_i32_f32_e32 v4, v4
	v_med3_i32 v1, v1, 0, v212
	v_med3_i32 v2, v2, 0, v212
	v_and_b32_e32 v6, 0xffff0000, v32
	v_lshlrev_b32_e32 v7, 16, v33
	v_med3_i32 v3, v3, 0, v212
	v_med3_i32 v4, v4, 0, v212
	v_lshl_or_b32 v1, v2, 8, v1
	v_lshlrev_b32_e32 v5, 16, v32
	v_and_b32_e32 v8, 0xffff0000, v33
	v_lshl_or_b32 v1, v3, 16, v1
	v_lshlrev_b32_e32 v2, 24, v4
	v_mul_f32_e32 v3, v44, v6
	v_mul_f32_e32 v4, v44, v7
	v_bitop3_b32 v2, v1, s57, v2 bitop3:0x36
	v_mul_f32_e32 v1, v44, v5
	v_rndne_f32_e32 v3, v3
	v_rndne_f32_e32 v4, v4
	v_mul_f32_e32 v5, v44, v8
	v_rndne_f32_e32 v1, v1
	v_cvt_i32_f32_e32 v3, v3
	v_cvt_i32_f32_e32 v4, v4
	v_rndne_f32_e32 v5, v5
	v_cvt_i32_f32_e32 v1, v1
	v_cvt_i32_f32_e32 v5, v5
	v_med3_i32 v3, v3, 0, v212
	v_med3_i32 v4, v4, 0, v212
	v_med3_i32 v1, v1, 0, v212
	v_med3_i32 v5, v5, 0, v212
	v_lshlrev_b32_e32 v3, 8, v3
	v_lshlrev_b32_e32 v4, 16, v4
	v_lshlrev_b32_e32 v9, 16, v26
	v_and_b32_e32 v10, 0xffff0000, v26
	v_or3_b32 v1, v3, v1, v4
	v_lshlrev_b32_e32 v3, 24, v5
	v_lshlrev_b32_e32 v11, 16, v27
	v_and_b32_e32 v12, 0xffff0000, v27
	v_bitop3_b32 v3, v1, s57, v3 bitop3:0x36
	v_mul_f32_e32 v1, v44, v9
	v_mul_f32_e32 v4, v44, v10
	v_rndne_f32_e32 v1, v1
	v_rndne_f32_e32 v4, v4
	v_mul_f32_e32 v5, v44, v11
	v_mul_f32_e32 v6, v44, v12
	v_cvt_i32_f32_e32 v1, v1
	v_cvt_i32_f32_e32 v4, v4
	v_rndne_f32_e32 v5, v5
	v_rndne_f32_e32 v6, v6
	v_cvt_i32_f32_e32 v5, v5
	v_cvt_i32_f32_e32 v6, v6
	v_med3_i32 v1, v1, 0, v212
	v_med3_i32 v4, v4, 0, v212
	v_and_b32_e32 v14, 0xffff0000, v28
	v_lshlrev_b32_e32 v15, 16, v29
	v_med3_i32 v5, v5, 0, v212
	v_med3_i32 v6, v6, 0, v212
	v_lshl_or_b32 v1, v4, 8, v1
	v_lshlrev_b32_e32 v13, 16, v28
	v_and_b32_e32 v16, 0xffff0000, v29
	v_lshl_or_b32 v1, v5, 16, v1
	v_lshlrev_b32_e32 v4, 24, v6
	v_mul_f32_e32 v5, v44, v14
	v_mul_f32_e32 v6, v44, v15
	v_bitop3_b32 v4, v1, s57, v4 bitop3:0x36
	v_mul_f32_e32 v1, v44, v13
	v_rndne_f32_e32 v5, v5
	v_rndne_f32_e32 v6, v6
	v_mul_f32_e32 v7, v44, v16
	v_rndne_f32_e32 v1, v1
	v_cvt_i32_f32_e32 v5, v5
	v_cvt_i32_f32_e32 v6, v6
	v_rndne_f32_e32 v7, v7
	v_cvt_i32_f32_e32 v1, v1
	v_cvt_i32_f32_e32 v7, v7
	v_med3_i32 v5, v5, 0, v212
	v_med3_i32 v6, v6, 0, v212
	v_med3_i32 v1, v1, 0, v212
	v_med3_i32 v7, v7, 0, v212
	v_lshlrev_b32_e32 v5, 8, v5
	v_lshlrev_b32_e32 v6, 16, v6
	v_or3_b32 v1, v5, v1, v6
	v_lshlrev_b32_e32 v5, 24, v7
	v_add_co_u32_e32 v6, vcc, 0x6000, v42
	s_add_i32 s11, s11, s86
	s_add_i32 s10, s10, s29
	v_bitop3_b32 v5, v1, s57, v5 bitop3:0x36
	v_addc_co_u32_e32 v7, vcc, 0, v43, vcc
	v_lshl_add_u64 v[40:41], v[40:41], 0, s[68:69]
	s_cmpk_gt_i32 s11, 0x1fff
	global_store_dwordx4 v[6:7], v[2:5], off
	s_cbranch_scc0 .LBB0_800
